# EpiResid + EpiMerge epilogues: in-place residual / gate / MERGED loads preloaded in one burst instead of per-block vmcnt(0) round trips; final-norm gains hoisted; conv waits relaxed
# speedup vs baseline: 1.0164x; 1.0044x over previous
; __device__ __forceinline__ u32x4 pack8(f32x4 a, f32x4 b) { u32x4 w; w.x = pk2(a[0], a[1]); w.y = pk2(a[2], a[3]); w.z = pk2(b[0], b[1]); w.w = pk2(b[2], b[3]); return w; }
; __device__ __forceinline__ void unpack8(u32x4 w, f32x4& a, f32x4& b) { a = (f32x4){bflo(w.x), bfhi(w.x), bflo(w.y), bfhi(w.y)}; b = (f32x4){bflo(w.z), bfhi(w.z), bflo(w.w), bfhi(w.w)}; }
;     __device__ __forceinline__ void operator()(const Acc& acc, const Unit& u, int wr, int wc, int fr, int fq, const RsCtx& rc) const {
; #pragma unroll
;         for (int ai = 0; ai < 2; ++ai)
; #pragma unroll
;             for (int m = 0; m < 4; ++m) { const int row = EPI_ROW(u, ai, wr, m, fr);
; #pragma unroll
;                 for (int bj = 0; bj < 2; ++bj) { const size_t off = (size_t)row * DM + u.pn * 256 + bj * 128 + wc * 32 + 8 * fq;
;                     const u32x2 gw = *(const u32x2*)(G + off); const float k255 = 1.0f / 255.0f;
;                     const f32x4 g0 = (f32x4){(float)(gw.x & 0xffu), (float)((gw.x >> 8) & 0xffu), (float)((gw.x >> 16) & 0xffu), (float)(gw.x >> 24)} * k255;
;                     const f32x4 g1 = (f32x4){(float)(gw.y & 0xffu), (float)((gw.y >> 8) & 0xffu), (float)((gw.y >> 16) & 0xffu), (float)(gw.y >> 24)} * k255;
;                     f32x4 v0 = g0 * acc[ai][bj][m][0], v1 = g1 * acc[ai][bj][m][1];
;                     if (!first) { f32x4 o0, o1; unpack8(*(const u32x4*)(Mg + off), o0, o1); v0 = v0 + o0; v1 = v1 + o1; }
;                     *(u32x4*)(Mg + off) = pack8(v0, v1); }
.LBB0_887:
	v_mov_b32_e32 v0, v153
	v_mov_b32_e32 v131, v154
	s_bitcmp0_b32 s12, 0
	v_lshlrev_b32_e32 v132, 3, v131
	v_ashrrev_i32_e32 v133, 31, v132
	s_mov_b64 s[4:5], -1
	s_cbranch_scc1 .LBB0_922
	s_cmp_lg_u32 s12, 1
	s_cselect_b64 s[22:23], -1, 0
	s_lshl_b32 s4, s76, 8
	s_add_i32 s4, s4, s68
	v_add_u32_e32 v136, s4, v0
	v_ashrrev_i32_e32 v137, 31, v136
	s_lshl_b32 s20, s13, 8
	v_lshl_add_u64 v[134:135], v[132:133], 0, s[10:11]
	v_lshlrev_b64 v[138:139], 10, v[136:137]
	s_ashr_i32 s21, s20, 31
	v_lshl_add_u64 v[138:139], v[138:139], 0, v[134:135]
	v_lshl_add_u64 v[148:149], v[138:139], 0, s[20:21]
	v_lshl_add_u64 v[140:141], s[44:45], 0, v[148:149]
	v_mov_b32_e32 v222, v148
	v_lshlrev_b32_e32 v223, 1, v148
	v_readlane_b32 s14, v255, 8
	v_readlane_b32 s15, v255, 9
	global_load_dwordx2 v[194:195], v222, s[44:45]
	global_load_dwordx2 v[206:207], v222, s[44:45] offset:128
	v_add_u32_e32 v242, 0x4000, v222
	global_load_dwordx2 v[208:209], v242, s[44:45]
	global_load_dwordx2 v[210:211], v242, s[44:45] offset:128
	v_add_u32_e32 v242, 0x8000, v222
	global_load_dwordx2 v[218:219], v242, s[44:45]
	global_load_dwordx2 v[220:221], v242, s[44:45] offset:128
	v_add_u32_e32 v242, 0xc000, v222
	global_load_dwordx2 v[236:237], v242, s[44:45]
	global_load_dwordx2 v[238:239], v242, s[44:45] offset:128
	s_andn2_b64 vcc, exec, s[22:23]
	s_cbranch_vccnz .Lmerge_nomA
	global_load_dwordx4 v[166:169], v223, s[14:15]
	global_load_dwordx4 v[170:173], v223, s[14:15] offset:256
	v_add_u32_e32 v243, 0x8000, v223
	global_load_dwordx4 v[174:177], v243, s[14:15]
	global_load_dwordx4 v[178:181], v243, s[14:15] offset:256
	v_add_u32_e32 v243, 0x10000, v223
	global_load_dwordx4 v[182:185], v243, s[14:15]
	global_load_dwordx4 v[186:189], v243, s[14:15] offset:256
	v_add_u32_e32 v243, 0x18000, v223
	global_load_dwordx4 v[190:193], v243, s[14:15]
	global_load_dwordx4 v[232:235], v243, s[14:15] offset:256
.Lmerge_nomA:
	s_mov_b32 s4, 0x3b808081
	s_cmp_eq_u32 s12, 1
	s_waitcnt vmcnt(0) lgkmcnt(0)
	v_mov_b64_e32 v[140:141], v[194:195]
	v_cvt_f32_ubyte3_e32 v143, v140
	v_cvt_f32_ubyte2_e32 v142, v140
	v_cvt_f32_ubyte1_e32 v145, v140
	v_cvt_f32_ubyte0_e32 v144, v140
	v_cvt_f32_ubyte3_e32 v147, v141
	v_cvt_f32_ubyte2_e32 v146, v141
	v_cvt_f32_ubyte1_e32 v159, v141
	v_cvt_f32_ubyte0_e32 v158, v141
	v_pk_mul_f32 v[144:145], v[144:145], s[4:5] op_sel_hi:[1,0]
	v_pk_mul_f32 v[140:141], v[142:143], s[4:5] op_sel_hi:[1,0]
	v_pk_mul_f32 v[158:159], v[158:159], s[4:5] op_sel_hi:[1,0]
	v_pk_mul_f32 v[146:147], v[146:147], s[4:5] op_sel_hi:[1,0]
	v_readlane_b32 s4, v255, 8
	v_readlane_b32 s5, v255, 9
	v_pk_mul_f32 v[140:141], v[128:129], v[140:141]
	v_pk_mul_f32 v[142:143], v[126:127], v[144:145]
	v_pk_mul_f32 v[144:145], v[124:125], v[146:147]
	v_pk_mul_f32 v[146:147], v[122:123], v[158:159]
	v_lshl_add_u64 v[148:149], v[148:149], 1, s[4:5]
	s_cbranch_scc1 .LBB0_890
	v_mov_b64_e32 v[158:159], v[166:167]
	v_mov_b64_e32 v[160:161], v[168:169]
	s_waitcnt lgkmcnt(0)
	v_lshlrev_b32_e32 v162, 16, v158
	v_and_b32_e32 v163, 0xffff0000, v158
	v_lshlrev_b32_e32 v158, 16, v159
	v_and_b32_e32 v159, 0xffff0000, v159
	v_lshlrev_b32_e32 v164, 16, v160
	v_and_b32_e32 v165, 0xffff0000, v160
	v_lshlrev_b32_e32 v160, 16, v161
	v_and_b32_e32 v161, 0xffff0000, v161
	v_pk_add_f32 v[140:141], v[140:141], v[158:159]
	v_pk_add_f32 v[142:143], v[142:143], v[162:163]
	v_pk_add_f32 v[144:145], v[144:145], v[160:161]
	v_pk_add_f32 v[146:147], v[146:147], v[164:165]
.LBB0_890:
	s_or_b32 s16, s20, 0x80
	s_mov_b32 s17, s21
	v_cvt_pk_bf16_f32 v158, v142, v143
	v_cvt_pk_bf16_f32 v159, v140, v141
	v_cvt_pk_bf16_f32 v160, v146, v147
	v_cvt_pk_bf16_f32 v161, v144, v145
	v_lshl_add_u64 v[138:139], v[138:139], 0, s[16:17]
	flat_store_dwordx4 v[148:149], v[158:161]
	v_lshl_add_u64 v[140:141], s[44:45], 0, v[138:139]
	v_mov_b64_e32 v[140:141], v[206:207]
	s_mov_b32 s12, 0x3b808081
	v_readlane_b32 s14, v255, 8
	v_cndmask_b32_e64 v131, 0, 1, s[22:23]
	v_readlane_b32 s15, v255, 9
	v_cmp_ne_u32_e64 s[4:5], 1, v131
	s_andn2_b64 vcc, exec, s[22:23]
	v_lshl_add_u64 v[138:139], v[138:139], 1, s[14:15]
	s_waitcnt lgkmcnt(0)
	v_cvt_f32_ubyte3_e32 v143, v140
	v_cvt_f32_ubyte2_e32 v142, v140
	v_cvt_f32_ubyte1_e32 v145, v140
	v_cvt_f32_ubyte0_e32 v144, v140
	v_cvt_f32_ubyte3_e32 v147, v141
	v_cvt_f32_ubyte2_e32 v146, v141
	v_cvt_f32_ubyte1_e32 v149, v141
	v_cvt_f32_ubyte0_e32 v148, v141
	v_pk_mul_f32 v[140:141], v[144:145], s[12:13] op_sel_hi:[1,0]
	v_pk_mul_f32 v[142:143], v[142:143], s[12:13] op_sel_hi:[1,0]
	v_pk_mul_f32 v[144:145], v[148:149], s[12:13] op_sel_hi:[1,0]
	v_pk_mul_f32 v[148:149], v[146:147], s[12:13] op_sel_hi:[1,0]
	v_pk_mul_f32 v[142:143], v[120:121], v[142:143]
	v_pk_mul_f32 v[146:147], v[118:119], v[140:141]
	v_pk_mul_f32 v[140:141], v[116:117], v[148:149]
	v_pk_mul_f32 v[144:145], v[114:115], v[144:145]
	s_cbranch_vccnz .LBB0_892
	v_mov_b64_e32 v[158:159], v[170:171]
	v_mov_b64_e32 v[160:161], v[172:173]
	s_waitcnt lgkmcnt(0)
	v_lshlrev_b32_e32 v148, 16, v158
	v_and_b32_e32 v149, 0xffff0000, v158
	v_lshlrev_b32_e32 v158, 16, v159
	v_and_b32_e32 v159, 0xffff0000, v159
	v_lshlrev_b32_e32 v162, 16, v160
	v_and_b32_e32 v163, 0xffff0000, v160
	v_lshlrev_b32_e32 v160, 16, v161
	v_and_b32_e32 v161, 0xffff0000, v161
	v_pk_add_f32 v[142:143], v[142:143], v[158:159]
	v_pk_add_f32 v[146:147], v[146:147], v[148:149]
	v_pk_add_f32 v[140:141], v[140:141], v[160:161]
	v_pk_add_f32 v[144:145], v[144:145], v[162:163]
; __device__ __forceinline__ u32x4 pack8(f32x4 a, f32x4 b) { u32x4 w; w.x = pk2(a[0], a[1]); w.y = pk2(a[2], a[3]); w.z = pk2(b[0], b[1]); w.w = pk2(b[2], b[3]); return w; }
; __device__ __forceinline__ void unpack8(u32x4 w, f32x4& a, f32x4& b) { a = (f32x4){bflo(w.x), bfhi(w.x), bflo(w.y), bfhi(w.y)}; b = (f32x4){bflo(w.z), bfhi(w.z), bflo(w.w), bfhi(w.w)}; }
;     __device__ __forceinline__ void operator()(const Acc& acc, const Unit& u, int wr, int wc, int fr, int fq, const RsCtx& rc) const {
; #pragma unroll
;         for (int ai = 0; ai < 2; ++ai)
; #pragma unroll
;             for (int m = 0; m < 4; ++m) { const int row = EPI_ROW(u, ai, wr, m, fr);
; #pragma unroll
;                 for (int bj = 0; bj < 2; ++bj) { const size_t off = (size_t)row * DM + u.pn * 256 + bj * 128 + wc * 32 + 8 * fq;
;                     const u32x2 gw = *(const u32x2*)(G + off); const float k255 = 1.0f / 255.0f;
;                     const f32x4 g0 = (f32x4){(float)(gw.x & 0xffu), (float)((gw.x >> 8) & 0xffu), (float)((gw.x >> 16) & 0xffu), (float)(gw.x >> 24)} * k255;
;                     const f32x4 g1 = (f32x4){(float)(gw.y & 0xffu), (float)((gw.y >> 8) & 0xffu), (float)((gw.y >> 16) & 0xffu), (float)(gw.y >> 24)} * k255;
;                     f32x4 v0 = g0 * acc[ai][bj][m][0], v1 = g1 * acc[ai][bj][m][1];
;                     if (!first) { f32x4 o0, o1; unpack8(*(const u32x4*)(Mg + off), o0, o1); v0 = v0 + o0; v1 = v1 + o1; }
;                     *(u32x4*)(Mg + off) = pack8(v0, v1); }
.LBB0_892:
	v_cvt_pk_bf16_f32 v146, v146, v147
	v_cvt_pk_bf16_f32 v147, v142, v143
	v_cvt_pk_bf16_f32 v148, v144, v145
	v_cvt_pk_bf16_f32 v149, v140, v141
	flat_store_dwordx4 v[138:139], v[146:149]
	v_add_u32_e32 v138, 16, v136
	v_ashrrev_i32_e32 v139, 31, v138
	v_lshlrev_b64 v[138:139], 10, v[138:139]
	v_lshl_add_u64 v[138:139], v[138:139], 0, v[134:135]
	v_lshl_add_u64 v[140:141], v[138:139], 0, s[20:21]
	v_lshl_add_u64 v[142:143], s[44:45], 0, v[140:141]
	v_mov_b64_e32 v[142:143], v[208:209]
	v_readlane_b32 s14, v255, 8
	v_readlane_b32 s15, v255, 9
	s_and_b64 vcc, exec, s[4:5]
	s_waitcnt lgkmcnt(0)
	v_cvt_f32_ubyte3_e32 v145, v142
	v_cvt_f32_ubyte2_e32 v144, v142
	v_cvt_f32_ubyte1_e32 v147, v142
	v_cvt_f32_ubyte0_e32 v146, v142
	v_cvt_f32_ubyte3_e32 v149, v143
	v_cvt_f32_ubyte2_e32 v148, v143
	v_cvt_f32_ubyte1_e32 v159, v143
	v_cvt_f32_ubyte0_e32 v158, v143
	v_pk_mul_f32 v[142:143], v[146:147], s[12:13] op_sel_hi:[1,0]
	v_pk_mul_f32 v[144:145], v[144:145], s[12:13] op_sel_hi:[1,0]
	v_pk_mul_f32 v[146:147], v[158:159], s[12:13] op_sel_hi:[1,0]
	v_pk_mul_f32 v[158:159], v[148:149], s[12:13] op_sel_hi:[1,0]
	v_pk_mul_f32 v[144:145], v[112:113], v[144:145]
	v_pk_mul_f32 v[148:149], v[110:111], v[142:143]
	v_pk_mul_f32 v[142:143], v[108:109], v[158:159]
	v_pk_mul_f32 v[146:147], v[106:107], v[146:147]
	v_lshl_add_u64 v[140:141], v[140:141], 1, s[14:15]
	s_cbranch_vccnz .LBB0_894
	v_mov_b64_e32 v[158:159], v[174:175]
	v_mov_b64_e32 v[160:161], v[176:177]
	s_waitcnt lgkmcnt(0)
	v_lshlrev_b32_e32 v162, 16, v158
	v_and_b32_e32 v163, 0xffff0000, v158
	v_lshlrev_b32_e32 v158, 16, v159
	v_and_b32_e32 v159, 0xffff0000, v159
	v_lshlrev_b32_e32 v164, 16, v160
	v_and_b32_e32 v165, 0xffff0000, v160
	v_lshlrev_b32_e32 v160, 16, v161
	v_and_b32_e32 v161, 0xffff0000, v161
	v_pk_add_f32 v[144:145], v[144:145], v[158:159]
	v_pk_add_f32 v[148:149], v[148:149], v[162:163]
	v_pk_add_f32 v[142:143], v[142:143], v[160:161]
	v_pk_add_f32 v[146:147], v[146:147], v[164:165]
.LBB0_894:
	v_cvt_pk_bf16_f32 v158, v148, v149
	v_cvt_pk_bf16_f32 v159, v144, v145
	v_cvt_pk_bf16_f32 v160, v146, v147
	v_cvt_pk_bf16_f32 v161, v142, v143
	v_lshl_add_u64 v[138:139], v[138:139], 0, s[16:17]
	flat_store_dwordx4 v[140:141], v[158:161]
	v_lshl_add_u64 v[140:141], s[44:45], 0, v[138:139]
	v_mov_b64_e32 v[140:141], v[210:211]
	v_readlane_b32 s14, v255, 8
	v_readlane_b32 s15, v255, 9
	s_and_b64 vcc, exec, s[4:5]
	s_waitcnt lgkmcnt(0)
	v_cvt_f32_ubyte3_e32 v143, v140
	v_cvt_f32_ubyte2_e32 v142, v140
	v_cvt_f32_ubyte1_e32 v145, v140
	v_cvt_f32_ubyte0_e32 v144, v140
	v_cvt_f32_ubyte3_e32 v147, v141
	v_cvt_f32_ubyte2_e32 v146, v141
	v_cvt_f32_ubyte1_e32 v149, v141
	v_cvt_f32_ubyte0_e32 v148, v141
	v_pk_mul_f32 v[140:141], v[144:145], s[12:13] op_sel_hi:[1,0]
	v_pk_mul_f32 v[142:143], v[142:143], s[12:13] op_sel_hi:[1,0]
	v_pk_mul_f32 v[144:145], v[148:149], s[12:13] op_sel_hi:[1,0]
	v_pk_mul_f32 v[148:149], v[146:147], s[12:13] op_sel_hi:[1,0]
	v_pk_mul_f32 v[142:143], v[104:105], v[142:143]
	v_pk_mul_f32 v[146:147], v[102:103], v[140:141]
	v_pk_mul_f32 v[140:141], v[100:101], v[148:149]
	v_pk_mul_f32 v[144:145], v[98:99], v[144:145]
	v_lshl_add_u64 v[138:139], v[138:139], 1, s[14:15]
	s_cbranch_vccnz .LBB0_896
	v_mov_b64_e32 v[158:159], v[178:179]
	v_mov_b64_e32 v[160:161], v[180:181]
	s_waitcnt lgkmcnt(0)
	v_lshlrev_b32_e32 v148, 16, v158
	v_and_b32_e32 v149, 0xffff0000, v158
	v_lshlrev_b32_e32 v158, 16, v159
	v_and_b32_e32 v159, 0xffff0000, v159
	v_lshlrev_b32_e32 v162, 16, v160
	v_and_b32_e32 v163, 0xffff0000, v160
	v_lshlrev_b32_e32 v160, 16, v161
	v_and_b32_e32 v161, 0xffff0000, v161
	v_pk_add_f32 v[142:143], v[142:143], v[158:159]
	v_pk_add_f32 v[146:147], v[146:147], v[148:149]
	v_pk_add_f32 v[140:141], v[140:141], v[160:161]
	v_pk_add_f32 v[144:145], v[144:145], v[162:163]
.LBB0_896:
	v_cvt_pk_bf16_f32 v146, v146, v147
	v_cvt_pk_bf16_f32 v147, v142, v143
	v_cvt_pk_bf16_f32 v148, v144, v145
	v_cvt_pk_bf16_f32 v149, v140, v141
	flat_store_dwordx4 v[138:139], v[146:149]
	v_add_u32_e32 v138, 32, v136
	v_ashrrev_i32_e32 v139, 31, v138
	v_lshlrev_b64 v[138:139], 10, v[138:139]
	v_lshl_add_u64 v[138:139], v[138:139], 0, v[134:135]
	v_lshl_add_u64 v[140:141], v[138:139], 0, s[20:21]
	v_lshl_add_u64 v[142:143], s[44:45], 0, v[140:141]
	v_mov_b64_e32 v[142:143], v[218:219]
	v_readlane_b32 s14, v255, 8
	v_readlane_b32 s15, v255, 9
	s_and_b64 vcc, exec, s[4:5]
	s_waitcnt lgkmcnt(0)
	v_cvt_f32_ubyte3_e32 v145, v142
	v_cvt_f32_ubyte2_e32 v144, v142
	v_cvt_f32_ubyte1_e32 v147, v142
	v_cvt_f32_ubyte0_e32 v146, v142
	v_cvt_f32_ubyte3_e32 v149, v143
	v_cvt_f32_ubyte2_e32 v148, v143
	v_cvt_f32_ubyte1_e32 v159, v143
	v_cvt_f32_ubyte0_e32 v158, v143
	v_pk_mul_f32 v[142:143], v[146:147], s[12:13] op_sel_hi:[1,0]
	v_pk_mul_f32 v[144:145], v[144:145], s[12:13] op_sel_hi:[1,0]
	v_pk_mul_f32 v[146:147], v[158:159], s[12:13] op_sel_hi:[1,0]
	v_pk_mul_f32 v[158:159], v[148:149], s[12:13] op_sel_hi:[1,0]
	v_pk_mul_f32 v[144:145], v[96:97], v[144:145]
	v_pk_mul_f32 v[148:149], v[94:95], v[142:143]
	v_pk_mul_f32 v[142:143], v[92:93], v[158:159]
	v_pk_mul_f32 v[146:147], v[90:91], v[146:147]
	v_lshl_add_u64 v[140:141], v[140:141], 1, s[14:15]
	s_cbranch_vccnz .LBB0_898
	v_mov_b64_e32 v[158:159], v[182:183]
	v_mov_b64_e32 v[160:161], v[184:185]
	s_waitcnt lgkmcnt(0)
	v_lshlrev_b32_e32 v162, 16, v158
	v_and_b32_e32 v163, 0xffff0000, v158
	v_lshlrev_b32_e32 v158, 16, v159
	v_and_b32_e32 v159, 0xffff0000, v159
	v_lshlrev_b32_e32 v164, 16, v160
	v_and_b32_e32 v165, 0xffff0000, v160
	v_lshlrev_b32_e32 v160, 16, v161
	v_and_b32_e32 v161, 0xffff0000, v161
	v_pk_add_f32 v[144:145], v[144:145], v[158:159]
	v_pk_add_f32 v[148:149], v[148:149], v[162:163]
	v_pk_add_f32 v[142:143], v[142:143], v[160:161]
	v_pk_add_f32 v[146:147], v[146:147], v[164:165]
; __device__ __forceinline__ u32x4 pack8(f32x4 a, f32x4 b) { u32x4 w; w.x = pk2(a[0], a[1]); w.y = pk2(a[2], a[3]); w.z = pk2(b[0], b[1]); w.w = pk2(b[2], b[3]); return w; }
; __device__ __forceinline__ void unpack8(u32x4 w, f32x4& a, f32x4& b) { a = (f32x4){bflo(w.x), bfhi(w.x), bflo(w.y), bfhi(w.y)}; b = (f32x4){bflo(w.z), bfhi(w.z), bflo(w.w), bfhi(w.w)}; }
;     __device__ __forceinline__ void operator()(const Acc& acc, const Unit& u, int wr, int wc, int fr, int fq, const RsCtx& rc) const {
; #pragma unroll
;         for (int ai = 0; ai < 2; ++ai)
; #pragma unroll
;             for (int m = 0; m < 4; ++m) { const int row = EPI_ROW(u, ai, wr, m, fr);
; #pragma unroll
;                 for (int bj = 0; bj < 2; ++bj) { const size_t off = (size_t)row * DM + u.pn * 256 + bj * 128 + wc * 32 + 8 * fq;
;                     const u32x2 gw = *(const u32x2*)(G + off); const float k255 = 1.0f / 255.0f;
;                     const f32x4 g0 = (f32x4){(float)(gw.x & 0xffu), (float)((gw.x >> 8) & 0xffu), (float)((gw.x >> 16) & 0xffu), (float)(gw.x >> 24)} * k255;
;                     const f32x4 g1 = (f32x4){(float)(gw.y & 0xffu), (float)((gw.y >> 8) & 0xffu), (float)((gw.y >> 16) & 0xffu), (float)(gw.y >> 24)} * k255;
;                     f32x4 v0 = g0 * acc[ai][bj][m][0], v1 = g1 * acc[ai][bj][m][1];
;                     if (!first) { f32x4 o0, o1; unpack8(*(const u32x4*)(Mg + off), o0, o1); v0 = v0 + o0; v1 = v1 + o1; }
;                     *(u32x4*)(Mg + off) = pack8(v0, v1); }
.LBB0_898:
	v_cvt_pk_bf16_f32 v158, v148, v149
	v_cvt_pk_bf16_f32 v159, v144, v145
	v_cvt_pk_bf16_f32 v160, v146, v147
	v_cvt_pk_bf16_f32 v161, v142, v143
	v_lshl_add_u64 v[138:139], v[138:139], 0, s[16:17]
	flat_store_dwordx4 v[140:141], v[158:161]
	v_lshl_add_u64 v[140:141], s[44:45], 0, v[138:139]
	v_mov_b64_e32 v[140:141], v[220:221]
	v_readlane_b32 s14, v255, 8
	v_readlane_b32 s15, v255, 9
	s_and_b64 vcc, exec, s[4:5]
	s_waitcnt lgkmcnt(0)
	v_cvt_f32_ubyte3_e32 v143, v140
	v_cvt_f32_ubyte2_e32 v142, v140
	v_cvt_f32_ubyte1_e32 v145, v140
	v_cvt_f32_ubyte0_e32 v144, v140
	v_cvt_f32_ubyte3_e32 v147, v141
	v_cvt_f32_ubyte2_e32 v146, v141
	v_cvt_f32_ubyte1_e32 v149, v141
	v_cvt_f32_ubyte0_e32 v148, v141
	v_pk_mul_f32 v[140:141], v[144:145], s[12:13] op_sel_hi:[1,0]
	v_pk_mul_f32 v[142:143], v[142:143], s[12:13] op_sel_hi:[1,0]
	v_pk_mul_f32 v[144:145], v[148:149], s[12:13] op_sel_hi:[1,0]
	v_pk_mul_f32 v[148:149], v[146:147], s[12:13] op_sel_hi:[1,0]
	v_pk_mul_f32 v[142:143], v[88:89], v[142:143]
	v_pk_mul_f32 v[146:147], v[86:87], v[140:141]
	v_pk_mul_f32 v[140:141], v[84:85], v[148:149]
	v_pk_mul_f32 v[144:145], v[82:83], v[144:145]
	v_lshl_add_u64 v[138:139], v[138:139], 1, s[14:15]
	s_cbranch_vccnz .LBB0_900
	v_mov_b64_e32 v[158:159], v[186:187]
	v_mov_b64_e32 v[160:161], v[188:189]
	s_waitcnt lgkmcnt(0)
	v_lshlrev_b32_e32 v148, 16, v158
	v_and_b32_e32 v149, 0xffff0000, v158
	v_lshlrev_b32_e32 v158, 16, v159
	v_and_b32_e32 v159, 0xffff0000, v159
	v_lshlrev_b32_e32 v162, 16, v160
	v_and_b32_e32 v163, 0xffff0000, v160
	v_lshlrev_b32_e32 v160, 16, v161
	v_and_b32_e32 v161, 0xffff0000, v161
	v_pk_add_f32 v[142:143], v[142:143], v[158:159]
	v_pk_add_f32 v[146:147], v[146:147], v[148:149]
	v_pk_add_f32 v[140:141], v[140:141], v[160:161]
	v_pk_add_f32 v[144:145], v[144:145], v[162:163]
.LBB0_900:
	v_cvt_pk_bf16_f32 v146, v146, v147
	v_cvt_pk_bf16_f32 v147, v142, v143
	v_cvt_pk_bf16_f32 v148, v144, v145
	v_cvt_pk_bf16_f32 v149, v140, v141
	flat_store_dwordx4 v[138:139], v[146:149]
	v_add_u32_e32 v138, 48, v136
	v_ashrrev_i32_e32 v139, 31, v138
	v_lshlrev_b64 v[138:139], 10, v[138:139]
	v_lshl_add_u64 v[138:139], v[138:139], 0, v[134:135]
	v_lshl_add_u64 v[140:141], v[138:139], 0, s[20:21]
	v_lshl_add_u64 v[142:143], s[44:45], 0, v[140:141]
	v_mov_b64_e32 v[142:143], v[236:237]
	v_readlane_b32 s14, v255, 8
	v_readlane_b32 s15, v255, 9
	s_and_b64 vcc, exec, s[4:5]
	s_waitcnt lgkmcnt(0)
	v_cvt_f32_ubyte3_e32 v145, v142
	v_cvt_f32_ubyte2_e32 v144, v142
	v_cvt_f32_ubyte1_e32 v147, v142
	v_cvt_f32_ubyte0_e32 v146, v142
	v_cvt_f32_ubyte3_e32 v149, v143
	v_cvt_f32_ubyte2_e32 v148, v143
	v_cvt_f32_ubyte1_e32 v159, v143
	v_cvt_f32_ubyte0_e32 v158, v143
	v_pk_mul_f32 v[142:143], v[146:147], s[12:13] op_sel_hi:[1,0]
	v_pk_mul_f32 v[144:145], v[144:145], s[12:13] op_sel_hi:[1,0]
	v_pk_mul_f32 v[146:147], v[158:159], s[12:13] op_sel_hi:[1,0]
	v_pk_mul_f32 v[158:159], v[148:149], s[12:13] op_sel_hi:[1,0]
	v_pk_mul_f32 v[144:145], v[80:81], v[144:145]
	v_pk_mul_f32 v[148:149], v[78:79], v[142:143]
	v_pk_mul_f32 v[142:143], v[76:77], v[158:159]
	v_pk_mul_f32 v[146:147], v[74:75], v[146:147]
	v_lshl_add_u64 v[140:141], v[140:141], 1, s[14:15]
	s_cbranch_vccnz .LBB0_902
	v_mov_b64_e32 v[158:159], v[190:191]
	v_mov_b64_e32 v[160:161], v[192:193]
	s_waitcnt lgkmcnt(0)
	v_lshlrev_b32_e32 v162, 16, v158
	v_and_b32_e32 v163, 0xffff0000, v158
	v_lshlrev_b32_e32 v158, 16, v159
	v_and_b32_e32 v159, 0xffff0000, v159
	v_lshlrev_b32_e32 v164, 16, v160
	v_and_b32_e32 v165, 0xffff0000, v160
	v_lshlrev_b32_e32 v160, 16, v161
	v_and_b32_e32 v161, 0xffff0000, v161
	v_pk_add_f32 v[144:145], v[144:145], v[158:159]
	v_pk_add_f32 v[148:149], v[148:149], v[162:163]
	v_pk_add_f32 v[142:143], v[142:143], v[160:161]
	v_pk_add_f32 v[146:147], v[146:147], v[164:165]
.LBB0_902:
	v_cvt_pk_bf16_f32 v158, v148, v149
	v_cvt_pk_bf16_f32 v159, v144, v145
	v_cvt_pk_bf16_f32 v160, v146, v147
	v_cvt_pk_bf16_f32 v161, v142, v143
	v_lshl_add_u64 v[138:139], v[138:139], 0, s[16:17]
	flat_store_dwordx4 v[140:141], v[158:161]
	v_lshl_add_u64 v[140:141], s[44:45], 0, v[138:139]
	v_mov_b64_e32 v[140:141], v[238:239]
	v_readlane_b32 s14, v255, 8
	v_readlane_b32 s15, v255, 9
	s_and_b64 vcc, exec, s[4:5]
	s_waitcnt lgkmcnt(0)
	v_cvt_f32_ubyte3_e32 v143, v140
	v_cvt_f32_ubyte2_e32 v142, v140
	v_cvt_f32_ubyte1_e32 v145, v140
	v_cvt_f32_ubyte0_e32 v144, v140
	v_cvt_f32_ubyte3_e32 v147, v141
	v_cvt_f32_ubyte2_e32 v146, v141
	v_cvt_f32_ubyte1_e32 v149, v141
	v_cvt_f32_ubyte0_e32 v148, v141
	v_pk_mul_f32 v[140:141], v[144:145], s[12:13] op_sel_hi:[1,0]
	v_pk_mul_f32 v[142:143], v[142:143], s[12:13] op_sel_hi:[1,0]
	v_pk_mul_f32 v[144:145], v[148:149], s[12:13] op_sel_hi:[1,0]
	v_pk_mul_f32 v[148:149], v[146:147], s[12:13] op_sel_hi:[1,0]
	v_pk_mul_f32 v[142:143], v[72:73], v[142:143]
	v_pk_mul_f32 v[146:147], v[70:71], v[140:141]
	v_pk_mul_f32 v[140:141], v[68:69], v[148:149]
	v_pk_mul_f32 v[144:145], v[66:67], v[144:145]
	v_lshl_add_u64 v[138:139], v[138:139], 1, s[14:15]
	s_cbranch_vccnz .LBB0_904
	v_mov_b64_e32 v[158:159], v[232:233]
	v_mov_b64_e32 v[160:161], v[234:235]
	s_waitcnt lgkmcnt(0)
	v_lshlrev_b32_e32 v148, 16, v158
	v_and_b32_e32 v149, 0xffff0000, v158
	v_lshlrev_b32_e32 v158, 16, v159
	v_and_b32_e32 v159, 0xffff0000, v159
	v_lshlrev_b32_e32 v162, 16, v160
	v_and_b32_e32 v163, 0xffff0000, v160
	v_lshlrev_b32_e32 v160, 16, v161
	v_and_b32_e32 v161, 0xffff0000, v161
	v_pk_add_f32 v[142:143], v[142:143], v[158:159]
	v_pk_add_f32 v[146:147], v[146:147], v[148:149]
	v_pk_add_f32 v[140:141], v[140:141], v[160:161]
	v_pk_add_f32 v[144:145], v[144:145], v[162:163]
; __device__ __forceinline__ u32x4 pack8(f32x4 a, f32x4 b) { u32x4 w; w.x = pk2(a[0], a[1]); w.y = pk2(a[2], a[3]); w.z = pk2(b[0], b[1]); w.w = pk2(b[2], b[3]); return w; }
; __device__ __forceinline__ void unpack8(u32x4 w, f32x4& a, f32x4& b) { a = (f32x4){bflo(w.x), bfhi(w.x), bflo(w.y), bfhi(w.y)}; b = (f32x4){bflo(w.z), bfhi(w.z), bflo(w.w), bfhi(w.w)}; }
;     __device__ __forceinline__ void operator()(const Acc& acc, const Unit& u, int wr, int wc, int fr, int fq, const RsCtx& rc) const {
; #pragma unroll
;         for (int ai = 0; ai < 2; ++ai)
; #pragma unroll
;             for (int m = 0; m < 4; ++m) { const int row = EPI_ROW(u, ai, wr, m, fr);
; #pragma unroll
;                 for (int bj = 0; bj < 2; ++bj) { const size_t off = (size_t)row * DM + u.pn * 256 + bj * 128 + wc * 32 + 8 * fq;
;                     const u32x2 gw = *(const u32x2*)(G + off); const float k255 = 1.0f / 255.0f;
;                     const f32x4 g0 = (f32x4){(float)(gw.x & 0xffu), (float)((gw.x >> 8) & 0xffu), (float)((gw.x >> 16) & 0xffu), (float)(gw.x >> 24)} * k255;
;                     const f32x4 g1 = (f32x4){(float)(gw.y & 0xffu), (float)((gw.y >> 8) & 0xffu), (float)((gw.y >> 16) & 0xffu), (float)(gw.y >> 24)} * k255;
;                     f32x4 v0 = g0 * acc[ai][bj][m][0], v1 = g1 * acc[ai][bj][m][1];
;                     if (!first) { f32x4 o0, o1; unpack8(*(const u32x4*)(Mg + off), o0, o1); v0 = v0 + o0; v1 = v1 + o1; }
;                     *(u32x4*)(Mg + off) = pack8(v0, v1); }
.LBB0_904:
	v_cvt_pk_bf16_f32 v146, v146, v147
	v_cvt_pk_bf16_f32 v147, v142, v143
	v_cvt_pk_bf16_f32 v148, v144, v145
	v_cvt_pk_bf16_f32 v149, v140, v141
	flat_store_dwordx4 v[138:139], v[146:149]
	v_add_u32_e32 v138, 0x80, v136
	v_ashrrev_i32_e32 v139, 31, v138
	v_lshlrev_b64 v[138:139], 10, v[138:139]
	v_lshl_add_u64 v[138:139], v[138:139], 0, v[134:135]
	v_lshl_add_u64 v[140:141], v[138:139], 0, s[20:21]
	v_lshl_add_u64 v[142:143], s[44:45], 0, v[140:141]
	v_readlane_b32 s14, v255, 8
	v_readlane_b32 s15, v255, 9
	v_add_u32_e32 v242, 0x20000, v222
	global_load_dwordx2 v[194:195], v242, s[44:45]
	global_load_dwordx2 v[206:207], v242, s[44:45] offset:128
	v_add_u32_e32 v242, 0x24000, v222
	global_load_dwordx2 v[208:209], v242, s[44:45]
	global_load_dwordx2 v[210:211], v242, s[44:45] offset:128
	v_add_u32_e32 v242, 0x28000, v222
	global_load_dwordx2 v[218:219], v242, s[44:45]
	global_load_dwordx2 v[220:221], v242, s[44:45] offset:128
	v_add_u32_e32 v242, 0x2c000, v222
	global_load_dwordx2 v[236:237], v242, s[44:45]
	global_load_dwordx2 v[238:239], v242, s[44:45] offset:128
	s_andn2_b64 vcc, exec, s[22:23]
	s_cbranch_vccnz .Lmerge_nomB
	v_add_u32_e32 v243, 0x40000, v223
	global_load_dwordx4 v[166:169], v243, s[14:15]
	global_load_dwordx4 v[170:173], v243, s[14:15] offset:256
	v_add_u32_e32 v243, 0x48000, v223
	global_load_dwordx4 v[174:177], v243, s[14:15]
	global_load_dwordx4 v[178:181], v243, s[14:15] offset:256
	v_add_u32_e32 v243, 0x50000, v223
	global_load_dwordx4 v[182:185], v243, s[14:15]
	global_load_dwordx4 v[186:189], v243, s[14:15] offset:256
	v_add_u32_e32 v243, 0x58000, v223
	global_load_dwordx4 v[190:193], v243, s[14:15]
	global_load_dwordx4 v[232:235], v243, s[14:15] offset:256
.Lmerge_nomB:
	v_readlane_b32 s14, v255, 8
	v_readlane_b32 s15, v255, 9
	s_and_b64 vcc, exec, s[4:5]
	s_waitcnt vmcnt(0) lgkmcnt(0)
	v_mov_b64_e32 v[142:143], v[194:195]
	v_cvt_f32_ubyte3_e32 v145, v142
	v_cvt_f32_ubyte2_e32 v144, v142
	v_cvt_f32_ubyte1_e32 v147, v142
	v_cvt_f32_ubyte0_e32 v146, v142
	v_cvt_f32_ubyte3_e32 v149, v143
	v_cvt_f32_ubyte2_e32 v148, v143
	v_cvt_f32_ubyte1_e32 v159, v143
	v_cvt_f32_ubyte0_e32 v158, v143
	v_pk_mul_f32 v[142:143], v[146:147], s[12:13] op_sel_hi:[1,0]
	v_pk_mul_f32 v[144:145], v[144:145], s[12:13] op_sel_hi:[1,0]
	v_pk_mul_f32 v[146:147], v[158:159], s[12:13] op_sel_hi:[1,0]
	v_pk_mul_f32 v[158:159], v[148:149], s[12:13] op_sel_hi:[1,0]
	v_pk_mul_f32 v[144:145], v[64:65], v[144:145]
	v_pk_mul_f32 v[148:149], v[62:63], v[142:143]
	v_pk_mul_f32 v[142:143], v[60:61], v[158:159]
	v_pk_mul_f32 v[146:147], v[58:59], v[146:147]
	v_lshl_add_u64 v[140:141], v[140:141], 1, s[14:15]
	s_cbranch_vccnz .LBB0_906
	v_mov_b64_e32 v[158:159], v[166:167]
	v_mov_b64_e32 v[160:161], v[168:169]
	s_waitcnt lgkmcnt(0)
	v_lshlrev_b32_e32 v162, 16, v158
	v_and_b32_e32 v163, 0xffff0000, v158
	v_lshlrev_b32_e32 v158, 16, v159
	v_and_b32_e32 v159, 0xffff0000, v159
	v_lshlrev_b32_e32 v164, 16, v160
	v_and_b32_e32 v165, 0xffff0000, v160
	v_lshlrev_b32_e32 v160, 16, v161
	v_and_b32_e32 v161, 0xffff0000, v161
	v_pk_add_f32 v[144:145], v[144:145], v[158:159]
	v_pk_add_f32 v[148:149], v[148:149], v[162:163]
	v_pk_add_f32 v[142:143], v[142:143], v[160:161]
	v_pk_add_f32 v[146:147], v[146:147], v[164:165]
.LBB0_906:
	v_cvt_pk_bf16_f32 v158, v148, v149
	v_cvt_pk_bf16_f32 v159, v144, v145
	v_cvt_pk_bf16_f32 v160, v146, v147
	v_cvt_pk_bf16_f32 v161, v142, v143
	v_lshl_add_u64 v[138:139], v[138:139], 0, s[16:17]
	flat_store_dwordx4 v[140:141], v[158:161]
	v_lshl_add_u64 v[140:141], s[44:45], 0, v[138:139]
	v_mov_b64_e32 v[140:141], v[206:207]
	v_readlane_b32 s14, v255, 8
	v_readlane_b32 s15, v255, 9
	s_and_b64 vcc, exec, s[4:5]
	s_waitcnt lgkmcnt(0)
	v_cvt_f32_ubyte3_e32 v143, v140
	v_cvt_f32_ubyte2_e32 v142, v140
	v_cvt_f32_ubyte1_e32 v145, v140
	v_cvt_f32_ubyte0_e32 v144, v140
	v_cvt_f32_ubyte3_e32 v147, v141
	v_cvt_f32_ubyte2_e32 v146, v141
	v_cvt_f32_ubyte1_e32 v149, v141
	v_cvt_f32_ubyte0_e32 v148, v141
	v_pk_mul_f32 v[140:141], v[144:145], s[12:13] op_sel_hi:[1,0]
	v_pk_mul_f32 v[142:143], v[142:143], s[12:13] op_sel_hi:[1,0]
	v_pk_mul_f32 v[144:145], v[148:149], s[12:13] op_sel_hi:[1,0]
	v_pk_mul_f32 v[148:149], v[146:147], s[12:13] op_sel_hi:[1,0]
	v_pk_mul_f32 v[142:143], v[56:57], v[142:143]
	v_pk_mul_f32 v[146:147], v[54:55], v[140:141]
	v_pk_mul_f32 v[140:141], v[52:53], v[148:149]
	v_pk_mul_f32 v[144:145], v[50:51], v[144:145]
	v_lshl_add_u64 v[138:139], v[138:139], 1, s[14:15]
	s_cbranch_vccnz .LBB0_908
	v_mov_b64_e32 v[158:159], v[170:171]
	v_mov_b64_e32 v[160:161], v[172:173]
	s_waitcnt lgkmcnt(0)
	v_lshlrev_b32_e32 v148, 16, v158
	v_and_b32_e32 v149, 0xffff0000, v158
	v_lshlrev_b32_e32 v158, 16, v159
	v_and_b32_e32 v159, 0xffff0000, v159
	v_lshlrev_b32_e32 v162, 16, v160
	v_and_b32_e32 v163, 0xffff0000, v160
	v_lshlrev_b32_e32 v160, 16, v161
	v_and_b32_e32 v161, 0xffff0000, v161
	v_pk_add_f32 v[142:143], v[142:143], v[158:159]
	v_pk_add_f32 v[146:147], v[146:147], v[148:149]
	v_pk_add_f32 v[140:141], v[140:141], v[160:161]
	v_pk_add_f32 v[144:145], v[144:145], v[162:163]
; __device__ __forceinline__ u32x4 pack8(f32x4 a, f32x4 b) { u32x4 w; w.x = pk2(a[0], a[1]); w.y = pk2(a[2], a[3]); w.z = pk2(b[0], b[1]); w.w = pk2(b[2], b[3]); return w; }
; __device__ __forceinline__ void unpack8(u32x4 w, f32x4& a, f32x4& b) { a = (f32x4){bflo(w.x), bfhi(w.x), bflo(w.y), bfhi(w.y)}; b = (f32x4){bflo(w.z), bfhi(w.z), bflo(w.w), bfhi(w.w)}; }
;     __device__ __forceinline__ void operator()(const Acc& acc, const Unit& u, int wr, int wc, int fr, int fq, const RsCtx& rc) const {
; #pragma unroll
;         for (int ai = 0; ai < 2; ++ai)
; #pragma unroll
;             for (int m = 0; m < 4; ++m) { const int row = EPI_ROW(u, ai, wr, m, fr);
; #pragma unroll
;                 for (int bj = 0; bj < 2; ++bj) { const size_t off = (size_t)row * DM + u.pn * 256 + bj * 128 + wc * 32 + 8 * fq;
;                     const u32x2 gw = *(const u32x2*)(G + off); const float k255 = 1.0f / 255.0f;
;                     const f32x4 g0 = (f32x4){(float)(gw.x & 0xffu), (float)((gw.x >> 8) & 0xffu), (float)((gw.x >> 16) & 0xffu), (float)(gw.x >> 24)} * k255;
;                     const f32x4 g1 = (f32x4){(float)(gw.y & 0xffu), (float)((gw.y >> 8) & 0xffu), (float)((gw.y >> 16) & 0xffu), (float)(gw.y >> 24)} * k255;
;                     f32x4 v0 = g0 * acc[ai][bj][m][0], v1 = g1 * acc[ai][bj][m][1];
;                     if (!first) { f32x4 o0, o1; unpack8(*(const u32x4*)(Mg + off), o0, o1); v0 = v0 + o0; v1 = v1 + o1; }
;                     *(u32x4*)(Mg + off) = pack8(v0, v1); }
.LBB0_908:
	v_cvt_pk_bf16_f32 v146, v146, v147
	v_cvt_pk_bf16_f32 v147, v142, v143
	v_cvt_pk_bf16_f32 v148, v144, v145
	v_cvt_pk_bf16_f32 v149, v140, v141
	flat_store_dwordx4 v[138:139], v[146:149]
	v_add_u32_e32 v138, 0x90, v136
	v_ashrrev_i32_e32 v139, 31, v138
	v_lshlrev_b64 v[138:139], 10, v[138:139]
	v_lshl_add_u64 v[138:139], v[138:139], 0, v[134:135]
	v_lshl_add_u64 v[140:141], v[138:139], 0, s[20:21]
	v_lshl_add_u64 v[142:143], s[44:45], 0, v[140:141]
	v_mov_b64_e32 v[142:143], v[208:209]
	v_readlane_b32 s14, v255, 8
	v_readlane_b32 s15, v255, 9
	s_and_b64 vcc, exec, s[4:5]
	s_waitcnt lgkmcnt(0)
	v_cvt_f32_ubyte3_e32 v145, v142
	v_cvt_f32_ubyte2_e32 v144, v142
	v_cvt_f32_ubyte1_e32 v147, v142
	v_cvt_f32_ubyte0_e32 v146, v142
	v_cvt_f32_ubyte3_e32 v149, v143
	v_cvt_f32_ubyte2_e32 v148, v143
	v_cvt_f32_ubyte1_e32 v159, v143
	v_cvt_f32_ubyte0_e32 v158, v143
	v_pk_mul_f32 v[142:143], v[146:147], s[12:13] op_sel_hi:[1,0]
	v_pk_mul_f32 v[144:145], v[144:145], s[12:13] op_sel_hi:[1,0]
	v_pk_mul_f32 v[146:147], v[158:159], s[12:13] op_sel_hi:[1,0]
	v_pk_mul_f32 v[158:159], v[148:149], s[12:13] op_sel_hi:[1,0]
	v_pk_mul_f32 v[144:145], v[48:49], v[144:145]
	v_pk_mul_f32 v[148:149], v[46:47], v[142:143]
	v_pk_mul_f32 v[142:143], v[44:45], v[158:159]
	v_pk_mul_f32 v[146:147], v[42:43], v[146:147]
	v_lshl_add_u64 v[140:141], v[140:141], 1, s[14:15]
	s_cbranch_vccnz .LBB0_910
	v_mov_b64_e32 v[158:159], v[174:175]
	v_mov_b64_e32 v[160:161], v[176:177]
	s_waitcnt lgkmcnt(0)
	v_lshlrev_b32_e32 v162, 16, v158
	v_and_b32_e32 v163, 0xffff0000, v158
	v_lshlrev_b32_e32 v158, 16, v159
	v_and_b32_e32 v159, 0xffff0000, v159
	v_lshlrev_b32_e32 v164, 16, v160
	v_and_b32_e32 v165, 0xffff0000, v160
	v_lshlrev_b32_e32 v160, 16, v161
	v_and_b32_e32 v161, 0xffff0000, v161
	v_pk_add_f32 v[144:145], v[144:145], v[158:159]
	v_pk_add_f32 v[148:149], v[148:149], v[162:163]
	v_pk_add_f32 v[142:143], v[142:143], v[160:161]
	v_pk_add_f32 v[146:147], v[146:147], v[164:165]
.LBB0_910:
	v_cvt_pk_bf16_f32 v158, v148, v149
	v_cvt_pk_bf16_f32 v159, v144, v145
	v_cvt_pk_bf16_f32 v160, v146, v147
	v_cvt_pk_bf16_f32 v161, v142, v143
	v_lshl_add_u64 v[138:139], v[138:139], 0, s[16:17]
	flat_store_dwordx4 v[140:141], v[158:161]
	v_lshl_add_u64 v[140:141], s[44:45], 0, v[138:139]
	v_mov_b64_e32 v[140:141], v[210:211]
	v_readlane_b32 s14, v255, 8
	v_readlane_b32 s15, v255, 9
	s_and_b64 vcc, exec, s[4:5]
	s_waitcnt lgkmcnt(0)
	v_cvt_f32_ubyte3_e32 v143, v140
	v_cvt_f32_ubyte2_e32 v142, v140
	v_cvt_f32_ubyte1_e32 v145, v140
	v_cvt_f32_ubyte0_e32 v144, v140
	v_cvt_f32_ubyte3_e32 v147, v141
	v_cvt_f32_ubyte2_e32 v146, v141
	v_cvt_f32_ubyte1_e32 v149, v141
	v_cvt_f32_ubyte0_e32 v148, v141
	v_pk_mul_f32 v[140:141], v[144:145], s[12:13] op_sel_hi:[1,0]
	v_pk_mul_f32 v[142:143], v[142:143], s[12:13] op_sel_hi:[1,0]
	v_pk_mul_f32 v[144:145], v[148:149], s[12:13] op_sel_hi:[1,0]
	v_pk_mul_f32 v[148:149], v[146:147], s[12:13] op_sel_hi:[1,0]
	v_pk_mul_f32 v[142:143], v[40:41], v[142:143]
	v_pk_mul_f32 v[146:147], v[38:39], v[140:141]
	v_pk_mul_f32 v[140:141], v[36:37], v[148:149]
	v_pk_mul_f32 v[144:145], v[34:35], v[144:145]
	v_lshl_add_u64 v[138:139], v[138:139], 1, s[14:15]
	s_cbranch_vccnz .LBB0_912
	v_mov_b64_e32 v[158:159], v[178:179]
	v_mov_b64_e32 v[160:161], v[180:181]
	s_waitcnt lgkmcnt(0)
	v_lshlrev_b32_e32 v148, 16, v158
	v_and_b32_e32 v149, 0xffff0000, v158
	v_lshlrev_b32_e32 v158, 16, v159
	v_and_b32_e32 v159, 0xffff0000, v159
	v_lshlrev_b32_e32 v162, 16, v160
	v_and_b32_e32 v163, 0xffff0000, v160
	v_lshlrev_b32_e32 v160, 16, v161
	v_and_b32_e32 v161, 0xffff0000, v161
	v_pk_add_f32 v[142:143], v[142:143], v[158:159]
	v_pk_add_f32 v[146:147], v[146:147], v[148:149]
	v_pk_add_f32 v[140:141], v[140:141], v[160:161]
	v_pk_add_f32 v[144:145], v[144:145], v[162:163]
.LBB0_912:
	v_cvt_pk_bf16_f32 v146, v146, v147
	v_cvt_pk_bf16_f32 v147, v142, v143
	v_cvt_pk_bf16_f32 v148, v144, v145
	v_cvt_pk_bf16_f32 v149, v140, v141
	flat_store_dwordx4 v[138:139], v[146:149]
	v_add_u32_e32 v138, 0xa0, v136
	v_ashrrev_i32_e32 v139, 31, v138
	v_lshlrev_b64 v[138:139], 10, v[138:139]
	v_lshl_add_u64 v[138:139], v[138:139], 0, v[134:135]
	v_lshl_add_u64 v[140:141], v[138:139], 0, s[20:21]
	v_lshl_add_u64 v[142:143], s[44:45], 0, v[140:141]
	v_mov_b64_e32 v[142:143], v[218:219]
	v_readlane_b32 s14, v255, 8
	v_readlane_b32 s15, v255, 9
	s_and_b64 vcc, exec, s[4:5]
	s_waitcnt lgkmcnt(0)
	v_cvt_f32_ubyte3_e32 v145, v142
	v_cvt_f32_ubyte2_e32 v144, v142
	v_cvt_f32_ubyte1_e32 v147, v142
	v_cvt_f32_ubyte0_e32 v146, v142
	v_cvt_f32_ubyte3_e32 v149, v143
	v_cvt_f32_ubyte2_e32 v148, v143
	v_cvt_f32_ubyte1_e32 v159, v143
	v_cvt_f32_ubyte0_e32 v158, v143
	v_pk_mul_f32 v[142:143], v[146:147], s[12:13] op_sel_hi:[1,0]
	v_pk_mul_f32 v[144:145], v[144:145], s[12:13] op_sel_hi:[1,0]
	v_pk_mul_f32 v[146:147], v[158:159], s[12:13] op_sel_hi:[1,0]
	v_pk_mul_f32 v[158:159], v[148:149], s[12:13] op_sel_hi:[1,0]
	v_pk_mul_f32 v[144:145], v[32:33], v[144:145]
	v_pk_mul_f32 v[148:149], v[30:31], v[142:143]
	v_pk_mul_f32 v[142:143], v[28:29], v[158:159]
	v_pk_mul_f32 v[146:147], v[26:27], v[146:147]
	v_lshl_add_u64 v[140:141], v[140:141], 1, s[14:15]
	s_cbranch_vccnz .LBB0_914
	v_mov_b64_e32 v[158:159], v[182:183]
	v_mov_b64_e32 v[160:161], v[184:185]
	s_waitcnt lgkmcnt(0)
	v_lshlrev_b32_e32 v162, 16, v158
	v_and_b32_e32 v163, 0xffff0000, v158
	v_lshlrev_b32_e32 v158, 16, v159
	v_and_b32_e32 v159, 0xffff0000, v159
	v_lshlrev_b32_e32 v164, 16, v160
	v_and_b32_e32 v165, 0xffff0000, v160
	v_lshlrev_b32_e32 v160, 16, v161
	v_and_b32_e32 v161, 0xffff0000, v161
	v_pk_add_f32 v[144:145], v[144:145], v[158:159]
	v_pk_add_f32 v[148:149], v[148:149], v[162:163]
	v_pk_add_f32 v[142:143], v[142:143], v[160:161]
	v_pk_add_f32 v[146:147], v[146:147], v[164:165]
; __device__ __forceinline__ u32x4 pack8(f32x4 a, f32x4 b) { u32x4 w; w.x = pk2(a[0], a[1]); w.y = pk2(a[2], a[3]); w.z = pk2(b[0], b[1]); w.w = pk2(b[2], b[3]); return w; }
; __device__ __forceinline__ void unpack8(u32x4 w, f32x4& a, f32x4& b) { a = (f32x4){bflo(w.x), bfhi(w.x), bflo(w.y), bfhi(w.y)}; b = (f32x4){bflo(w.z), bfhi(w.z), bflo(w.w), bfhi(w.w)}; }
;     __device__ __forceinline__ void operator()(const Acc& acc, const Unit& u, int wr, int wc, int fr, int fq, const RsCtx& rc) const {
;     ...
;             for (int m = 0; m < 4; ++m) { const int row = EPI_ROW(u, ai, wr, m, fr);
; #pragma unroll
;                 for (int bj = 0; bj < 2; ++bj) { const size_t off = (size_t)row * DM + u.pn * 256 + bj * 128 + wc * 32 + 8 * fq;
;                     const u32x2 gw = *(const u32x2*)(G + off); const float k255 = 1.0f / 255.0f;
;                     const f32x4 g0 = (f32x4){(float)(gw.x & 0xffu), (float)((gw.x >> 8) & 0xffu), (float)((gw.x >> 16) & 0xffu), (float)(gw.x >> 24)} * k255;
;                     const f32x4 g1 = (f32x4){(float)(gw.y & 0xffu), (float)((gw.y >> 8) & 0xffu), (float)((gw.y >> 16) & 0xffu), (float)(gw.y >> 24)} * k255;
;                     f32x4 v0 = g0 * acc[ai][bj][m][0], v1 = g1 * acc[ai][bj][m][1];
;                     if (!first) { f32x4 o0, o1; unpack8(*(const u32x4*)(Mg + off), o0, o1); v0 = v0 + o0; v1 = v1 + o1; }
;                     *(u32x4*)(Mg + off) = pack8(v0, v1); }
.LBB0_914:
	v_cvt_pk_bf16_f32 v158, v148, v149
	v_cvt_pk_bf16_f32 v159, v144, v145
	v_cvt_pk_bf16_f32 v160, v146, v147
	v_cvt_pk_bf16_f32 v161, v142, v143
	v_lshl_add_u64 v[138:139], v[138:139], 0, s[16:17]
	flat_store_dwordx4 v[140:141], v[158:161]
	v_lshl_add_u64 v[140:141], s[44:45], 0, v[138:139]
	v_mov_b64_e32 v[140:141], v[220:221]
	v_readlane_b32 s14, v255, 8
	v_readlane_b32 s15, v255, 9
	s_and_b64 vcc, exec, s[4:5]
	s_waitcnt lgkmcnt(0)
	v_cvt_f32_ubyte3_e32 v143, v140
	v_cvt_f32_ubyte2_e32 v142, v140
	v_cvt_f32_ubyte1_e32 v145, v140
	v_cvt_f32_ubyte0_e32 v144, v140
	v_cvt_f32_ubyte3_e32 v147, v141
	v_cvt_f32_ubyte2_e32 v146, v141
	v_cvt_f32_ubyte1_e32 v149, v141
	v_cvt_f32_ubyte0_e32 v148, v141
	v_pk_mul_f32 v[140:141], v[144:145], s[12:13] op_sel_hi:[1,0]
	v_pk_mul_f32 v[142:143], v[142:143], s[12:13] op_sel_hi:[1,0]
	v_pk_mul_f32 v[144:145], v[148:149], s[12:13] op_sel_hi:[1,0]
	v_pk_mul_f32 v[148:149], v[146:147], s[12:13] op_sel_hi:[1,0]
	v_pk_mul_f32 v[142:143], v[24:25], v[142:143]
	v_pk_mul_f32 v[146:147], v[22:23], v[140:141]
	v_pk_mul_f32 v[140:141], v[20:21], v[148:149]
	v_pk_mul_f32 v[144:145], v[18:19], v[144:145]
	v_lshl_add_u64 v[138:139], v[138:139], 1, s[14:15]
	s_cbranch_vccnz .LBB0_916
	v_mov_b64_e32 v[158:159], v[186:187]
	v_mov_b64_e32 v[160:161], v[188:189]
	s_waitcnt lgkmcnt(0)
	v_lshlrev_b32_e32 v148, 16, v158
	v_and_b32_e32 v149, 0xffff0000, v158
	v_lshlrev_b32_e32 v158, 16, v159
	v_and_b32_e32 v159, 0xffff0000, v159
	v_lshlrev_b32_e32 v162, 16, v160
	v_and_b32_e32 v163, 0xffff0000, v160
	v_lshlrev_b32_e32 v160, 16, v161
	v_and_b32_e32 v161, 0xffff0000, v161
	v_pk_add_f32 v[142:143], v[142:143], v[158:159]
	v_pk_add_f32 v[146:147], v[146:147], v[148:149]
	v_pk_add_f32 v[140:141], v[140:141], v[160:161]
	v_pk_add_f32 v[144:145], v[144:145], v[162:163]
.LBB0_916:
	v_add_u32_e32 v136, 0xb0, v136
	v_ashrrev_i32_e32 v137, 31, v136
	v_lshlrev_b64 v[136:137], 10, v[136:137]
	v_lshl_add_u64 v[134:135], v[136:137], 0, v[134:135]
	v_cvt_pk_bf16_f32 v146, v146, v147
	v_cvt_pk_bf16_f32 v147, v142, v143
	v_cvt_pk_bf16_f32 v148, v144, v145
	v_cvt_pk_bf16_f32 v149, v140, v141
	v_lshl_add_u64 v[136:137], v[134:135], 0, s[20:21]
	flat_store_dwordx4 v[138:139], v[146:149]
	v_lshl_add_u64 v[138:139], s[44:45], 0, v[136:137]
	v_mov_b64_e32 v[138:139], v[236:237]
	v_readlane_b32 s14, v255, 8
	v_readlane_b32 s15, v255, 9
	s_and_b64 vcc, exec, s[4:5]
	s_waitcnt lgkmcnt(0)
	v_cvt_f32_ubyte3_e32 v141, v138
	v_cvt_f32_ubyte2_e32 v140, v138
	v_cvt_f32_ubyte1_e32 v143, v138
	v_cvt_f32_ubyte0_e32 v142, v138
	v_cvt_f32_ubyte3_e32 v145, v139
	v_cvt_f32_ubyte2_e32 v144, v139
	v_cvt_f32_ubyte1_e32 v147, v139
	v_cvt_f32_ubyte0_e32 v146, v139
	v_pk_mul_f32 v[138:139], v[142:143], s[12:13] op_sel_hi:[1,0]
	v_pk_mul_f32 v[140:141], v[140:141], s[12:13] op_sel_hi:[1,0]
	v_pk_mul_f32 v[142:143], v[146:147], s[12:13] op_sel_hi:[1,0]
	v_pk_mul_f32 v[146:147], v[144:145], s[12:13] op_sel_hi:[1,0]
	v_pk_mul_f32 v[140:141], v[16:17], v[140:141]
	v_pk_mul_f32 v[144:145], v[14:15], v[138:139]
	v_pk_mul_f32 v[138:139], v[12:13], v[146:147]
	v_pk_mul_f32 v[142:143], v[10:11], v[142:143]
	v_lshl_add_u64 v[136:137], v[136:137], 1, s[14:15]
	s_cbranch_vccnz .LBB0_918
	v_mov_b64_e32 v[146:147], v[190:191]
	v_mov_b64_e32 v[148:149], v[192:193]
	s_waitcnt lgkmcnt(0)
	v_lshlrev_b32_e32 v158, 16, v146
	v_and_b32_e32 v159, 0xffff0000, v146
	v_lshlrev_b32_e32 v146, 16, v147
	v_and_b32_e32 v147, 0xffff0000, v147
	v_lshlrev_b32_e32 v160, 16, v148
	v_and_b32_e32 v161, 0xffff0000, v148
	v_lshlrev_b32_e32 v148, 16, v149
	v_and_b32_e32 v149, 0xffff0000, v149
	v_pk_add_f32 v[140:141], v[140:141], v[146:147]
	v_pk_add_f32 v[144:145], v[144:145], v[158:159]
	v_pk_add_f32 v[138:139], v[138:139], v[148:149]
	v_pk_add_f32 v[142:143], v[142:143], v[160:161]
.LBB0_918:
	v_cvt_pk_bf16_f32 v144, v144, v145
	v_cvt_pk_bf16_f32 v145, v140, v141
	v_cvt_pk_bf16_f32 v146, v142, v143
	v_cvt_pk_bf16_f32 v147, v138, v139
	v_lshl_add_u64 v[134:135], v[134:135], 0, s[16:17]
	flat_store_dwordx4 v[136:137], v[144:147]
	v_lshl_add_u64 v[136:137], s[44:45], 0, v[134:135]
	v_mov_b64_e32 v[136:137], v[238:239]
	s_and_b64 vcc, exec, s[4:5]
	s_mov_b32 s4, 0x3b808081
	s_waitcnt lgkmcnt(0)
	v_cvt_f32_ubyte3_e32 v139, v136
	v_cvt_f32_ubyte2_e32 v138, v136
	v_cvt_f32_ubyte1_e32 v141, v136
	v_cvt_f32_ubyte0_e32 v140, v136
	v_cvt_f32_ubyte3_e32 v143, v137
	v_cvt_f32_ubyte2_e32 v142, v137
	v_cvt_f32_ubyte1_e32 v145, v137
	v_cvt_f32_ubyte0_e32 v144, v137
	v_pk_mul_f32 v[136:137], v[140:141], s[4:5] op_sel_hi:[1,0]
	v_pk_mul_f32 v[138:139], v[138:139], s[4:5] op_sel_hi:[1,0]
	v_pk_mul_f32 v[140:141], v[144:145], s[4:5] op_sel_hi:[1,0]
	v_pk_mul_f32 v[144:145], v[142:143], s[4:5] op_sel_hi:[1,0]
	v_readlane_b32 s4, v255, 8
	v_readlane_b32 s5, v255, 9
	v_pk_mul_f32 v[138:139], v[8:9], v[138:139]
	v_pk_mul_f32 v[142:143], v[6:7], v[136:137]
	v_pk_mul_f32 v[136:137], v[4:5], v[144:145]
	v_pk_mul_f32 v[140:141], v[2:3], v[140:141]
	v_lshl_add_u64 v[134:135], v[134:135], 1, s[4:5]
	s_cbranch_vccnz .LBB0_920
	v_mov_b64_e32 v[144:145], v[232:233]
	v_mov_b64_e32 v[146:147], v[234:235]
	s_waitcnt lgkmcnt(0)
	v_lshlrev_b32_e32 v148, 16, v144
	v_and_b32_e32 v149, 0xffff0000, v144
	v_lshlrev_b32_e32 v144, 16, v145
	v_and_b32_e32 v145, 0xffff0000, v145
	v_lshlrev_b32_e32 v158, 16, v146
	v_and_b32_e32 v159, 0xffff0000, v146
	v_lshlrev_b32_e32 v146, 16, v147
	v_and_b32_e32 v147, 0xffff0000, v147
	v_pk_add_f32 v[138:139], v[138:139], v[144:145]
	v_pk_add_f32 v[142:143], v[142:143], v[148:149]
	v_pk_add_f32 v[136:137], v[136:137], v[146:147]
	v_pk_add_f32 v[140:141], v[140:141], v[158:159]
